# attention far64 tiles: V^T fragment LDS reads issued 4 (selected) / 6 (window) ahead of their PV MFMAs using dead VGPRs
# speedup vs baseline: 1.0035x; 1.0035x over previous
; DI float xor32_max(float x) { const auto r_ = __builtin_amdgcn_permlane32_swap(__float_as_uint(x), __float_as_uint(x), false, false); return fmaxf(__uint_as_float(r_[0]), __uint_as_float(r_[1])); }
; #define MFMA32(a, b, c) __builtin_amdgcn_mfma_f32_32x32x16_bf16((a), (b), (c), 0, 0, 0)
; template <int MODE>
; DI void attn_tile64_far(const unsigned char* bp  , int r, int hh, bool bit, const bf16x8 (&qf)[8], const float* lutH, f32x16 (&o)[4], float& m, float& l) {
;     f32x16 s0, s1;
; #pragma unroll
;     for (int i = 0; i < 16; ++i) { s0[i] = 0.f; s1[i] = 0.f; }
;     const unsigned char* kp = bp + r * 272 + 16 * hh;
; #pragma unroll
;     for (int kk = 0; kk < 8; ++kk) { const bf16x8 a0 = *(const bf16x8*)(kp + 32 * kk), a1 = *(const bf16x8*)(kp + 32 * 272 + 32 * kk); s0 = MFMA32(a0, qf[kk], s0); s1 = MFMA32(a1, qf[kk], s1); }
;     const float b31 = lutH[255];
;     float tmax = NEGF;
; #pragma unroll
;     for (int i = 0; i < 16; ++i) { s0[i] = s0[i] * QK_C1 + b31; s1[i] = s1[i] * QK_C1 + b31; tmax = fmaxf(tmax, fmaxf(s0[i], s1[i])); }
;     if (MODE == 0 && !bit) tmax = NEGF;
;     tmax = xor32_max(tmax);
;     const float mnew = fmaxf(m, tmax);
;     const float msub = (MODE == 0 && !bit) ? 3.0e38f : mnew;
;     if (__ballot(mnew != m) != 0ull) {
;         const float alpha = __builtin_amdgcn_exp2f(m - mnew);
;         l *= alpha; m = mnew;
; #pragma unroll
;         for (int dt = 0; dt < 4; ++dt)
; #pragma unroll
;             for (int i = 0; i < 16; ++i) o[dt][i] *= alpha;
;     }
.LBB0_801:
.LBB0_802:
	s_andn2_saveexec_b64 s[14:15], s[16:17]
	s_cbranch_execz .LBB0_806
	s_waitcnt lgkmcnt(0)
	ds_read_b32 v4, v202 offset:1020
	ds_read_b128 v[6:9], v2
	ds_read_b128 v[10:13], v2 offset:8704
	ds_read_b128 v[214:217], v2 offset:32
	ds_read_b128 v[218:221], v2 offset:8736
	ds_read_b128 v[224:227], v2 offset:64
	ds_read_b128 v[228:231], v2 offset:8768
	ds_read_b128 v[232:235], v2 offset:96
	ds_read_b128 v[236:239], v2 offset:8800
	s_waitcnt lgkmcnt(7)
	v_mfma_f32_32x32x16_bf16 v[82:97], v[6:9], v[114:117], 0
	ds_read_b128 v[240:243], v2 offset:128
	s_waitcnt lgkmcnt(7)
	v_mfma_f32_32x32x16_bf16 v[98:113], v[10:13], v[114:117], 0
	ds_read_b128 v[6:9], v2 offset:8832
	s_waitcnt lgkmcnt(7)
	v_mfma_f32_32x32x16_bf16 v[82:97], v[214:217], v[118:121], v[82:97]
	ds_read_b128 v[10:13], v2 offset:160
	s_waitcnt lgkmcnt(7)
	v_mfma_f32_32x32x16_bf16 v[98:113], v[218:221], v[118:121], v[98:113]
	ds_read_b128 v[214:217], v2 offset:8864
	s_waitcnt lgkmcnt(7)
	v_mfma_f32_32x32x16_bf16 v[82:97], v[224:227], v[122:125], v[82:97]
	ds_read_b128 v[218:221], v2 offset:192
	s_waitcnt lgkmcnt(7)
	v_mfma_f32_32x32x16_bf16 v[98:113], v[228:231], v[122:125], v[98:113]
	ds_read_b128 v[224:227], v2 offset:8896
	s_waitcnt lgkmcnt(7)
	v_mfma_f32_32x32x16_bf16 v[82:97], v[232:235], v[126:129], v[82:97]
	ds_read_b128 v[228:231], v2 offset:224
	s_waitcnt lgkmcnt(7)
	v_mfma_f32_32x32x16_bf16 v[98:113], v[236:239], v[126:129], v[98:113]
	ds_read_b128 v[232:235], v2 offset:8928
	s_waitcnt lgkmcnt(7)
	v_mfma_f32_32x32x16_bf16 v[82:97], v[240:243], v[130:133], v[82:97]
	s_waitcnt lgkmcnt(6)
	v_mfma_f32_32x32x16_bf16 v[98:113], v[6:9], v[130:133], v[98:113]
	s_waitcnt lgkmcnt(5)
	v_mfma_f32_32x32x16_bf16 v[82:97], v[10:13], v[134:137], v[82:97]
	s_waitcnt lgkmcnt(4)
	v_mfma_f32_32x32x16_bf16 v[98:113], v[214:217], v[134:137], v[98:113]
	s_waitcnt lgkmcnt(3)
	v_mfma_f32_32x32x16_bf16 v[82:97], v[218:221], v[138:141], v[82:97]
	s_waitcnt lgkmcnt(2)
	v_mfma_f32_32x32x16_bf16 v[98:113], v[224:227], v[138:141], v[98:113]
	s_waitcnt lgkmcnt(1)
	v_mfma_f32_32x32x16_bf16 v[82:97], v[228:231], v[142:145], v[82:97]
	s_waitcnt lgkmcnt(0)
	v_mfma_f32_32x32x16_bf16 v[98:113], v[232:235], v[142:145], v[98:113]
	s_nop 9
	v_add_u32_e32 v240, 0x4000, v187
	v_add_u32_e32 v241, 0x5000, v187
	v_add_u32_e32 v242, 0x6000, v187
	v_add_u32_e32 v243, 0x7000, v187
	ds_read2_b64 v[224:227], v240 offset0:128 offset1:130
	ds_read2_b64 v[228:231], v240 offset0:136 offset1:138
	ds_read2_b64 v[232:235], v241 offset0:160 offset1:162
	ds_read2_b64 v[236:239], v241 offset0:168 offset1:170
	v_fmamk_f32 v219, v82, 0x3e0293ee, v4
	v_fmamk_f32 v218, v83, 0x3e0293ee, v4
	v_fmamk_f32 v217, v84, 0x3e0293ee, v4
	v_fmamk_f32 v215, v85, 0x3e0293ee, v4
	v_fmamk_f32 v213, v86, 0x3e0293ee, v4
	v_fmamk_f32 v85, v90, 0x3e0293ee, v4
	v_fmamk_f32 v84, v91, 0x3e0293ee, v4
	v_fmamk_f32 v220, v98, 0x3e0293ee, v4
	v_fmamk_f32 v2, v99, 0x3e0293ee, v4
	v_max_f32_e32 v5, v219, v220
	v_max_f32_e32 v6, v218, v2
	v_fmamk_f32 v216, v100, 0x3e0293ee, v4
	v_fmamk_f32 v214, v101, 0x3e0293ee, v4
	v_max3_f32 v5, v5, s49, v6
	v_max_f32_e32 v6, v217, v216
	v_max_f32_e32 v7, v215, v214
	v_fmamk_f32 v101, v102, 0x3e0293ee, v4
	v_fmamk_f32 v100, v87, 0x3e0293ee, v4
	v_fmamk_f32 v99, v103, 0x3e0293ee, v4
	v_max3_f32 v5, v5, v6, v7
	v_max_f32_e32 v6, v213, v101
	v_max_f32_e32 v7, v100, v99
	v_fmamk_f32 v98, v88, 0x3e0293ee, v4
	v_fmamk_f32 v88, v104, 0x3e0293ee, v4
	v_fmamk_f32 v87, v89, 0x3e0293ee, v4
	v_fmamk_f32 v86, v105, 0x3e0293ee, v4
	v_max3_f32 v5, v5, v6, v7
	v_max_f32_e32 v6, v98, v88
	v_max_f32_e32 v7, v87, v86
	v_fmamk_f32 v83, v106, 0x3e0293ee, v4
	v_fmamk_f32 v82, v107, 0x3e0293ee, v4
	v_max3_f32 v5, v5, v6, v7
	v_max_f32_e32 v6, v85, v83
	v_max_f32_e32 v7, v84, v82
	v_fmamk_f32 v15, v92, 0x3e0293ee, v4
	v_fmamk_f32 v13, v108, 0x3e0293ee, v4
	v_fmamk_f32 v14, v93, 0x3e0293ee, v4
	v_fmamk_f32 v12, v109, 0x3e0293ee, v4
	v_max3_f32 v5, v5, v6, v7
	v_max_f32_e32 v6, v15, v13
	v_max_f32_e32 v7, v14, v12
	v_fmamk_f32 v11, v94, 0x3e0293ee, v4
	v_fmamk_f32 v9, v110, 0x3e0293ee, v4
	v_fmamk_f32 v10, v95, 0x3e0293ee, v4
	v_fmamk_f32 v8, v111, 0x3e0293ee, v4
	v_max3_f32 v5, v5, v6, v7
	v_max_f32_e32 v6, v11, v9
	v_max_f32_e32 v7, v10, v8
	v_max3_f32 v89, v5, v6, v7
	v_fmamk_f32 v7, v96, 0x3e0293ee, v4
	v_fmamk_f32 v6, v112, 0x3e0293ee, v4
	v_fmamk_f32 v5, v97, 0x3e0293ee, v4
	v_fmac_f32_e32 v4, 0x3e0293ee, v113
	v_max_f32_e32 v90, v7, v6
	v_max_f32_e32 v91, v5, v4
	v_max3_f32 v89, v89, v90, v91
	v_cndmask_b32_e64 v89, v195, v89, s[10:11]
	v_mov_b32_e32 v90, v89
	s_nop 1
	v_permlane32_swap_b32_e32 v89, v90
	v_max3_f32 v89, v212, v89, v90
	v_cmp_neq_f32_e32 vcc, v89, v212
	s_cbranch_vccz .LBB0_805
	v_sub_f32_e32 v90, v212, v89
	v_exp_f32_e32 v90, v90
	v_mov_b32_e32 v212, v89
	v_mul_f32_e32 v181, v181, v90
	v_pk_mul_f32 v[80:81], v[80:81], v[90:91] op_sel_hi:[1,0]
	v_pk_mul_f32 v[78:79], v[78:79], v[90:91] op_sel_hi:[1,0]
	v_pk_mul_f32 v[76:77], v[76:77], v[90:91] op_sel_hi:[1,0]
	v_pk_mul_f32 v[74:75], v[74:75], v[90:91] op_sel_hi:[1,0]
	v_pk_mul_f32 v[72:73], v[72:73], v[90:91] op_sel_hi:[1,0]
	v_pk_mul_f32 v[70:71], v[70:71], v[90:91] op_sel_hi:[1,0]
	v_pk_mul_f32 v[68:69], v[68:69], v[90:91] op_sel_hi:[1,0]
	v_pk_mul_f32 v[66:67], v[66:67], v[90:91] op_sel_hi:[1,0]
	v_pk_mul_f32 v[64:65], v[64:65], v[90:91] op_sel_hi:[1,0]
	v_pk_mul_f32 v[62:63], v[62:63], v[90:91] op_sel_hi:[1,0]
	v_pk_mul_f32 v[60:61], v[60:61], v[90:91] op_sel_hi:[1,0]
	v_pk_mul_f32 v[58:59], v[58:59], v[90:91] op_sel_hi:[1,0]
	v_pk_mul_f32 v[56:57], v[56:57], v[90:91] op_sel_hi:[1,0]
	v_pk_mul_f32 v[54:55], v[54:55], v[90:91] op_sel_hi:[1,0]
	v_pk_mul_f32 v[52:53], v[52:53], v[90:91] op_sel_hi:[1,0]
	v_pk_mul_f32 v[50:51], v[50:51], v[90:91] op_sel_hi:[1,0]
	v_pk_mul_f32 v[48:49], v[48:49], v[90:91] op_sel_hi:[1,0]
	v_pk_mul_f32 v[46:47], v[46:47], v[90:91] op_sel_hi:[1,0]
	v_pk_mul_f32 v[44:45], v[44:45], v[90:91] op_sel_hi:[1,0]
	v_pk_mul_f32 v[42:43], v[42:43], v[90:91] op_sel_hi:[1,0]
	v_pk_mul_f32 v[40:41], v[40:41], v[90:91] op_sel_hi:[1,0]
	v_pk_mul_f32 v[38:39], v[38:39], v[90:91] op_sel_hi:[1,0]
	v_pk_mul_f32 v[36:37], v[36:37], v[90:91] op_sel_hi:[1,0]
	v_pk_mul_f32 v[34:35], v[34:35], v[90:91] op_sel_hi:[1,0]
	v_pk_mul_f32 v[32:33], v[32:33], v[90:91] op_sel_hi:[1,0]
	v_pk_mul_f32 v[30:31], v[30:31], v[90:91] op_sel_hi:[1,0]
	v_pk_mul_f32 v[28:29], v[28:29], v[90:91] op_sel_hi:[1,0]
	v_pk_mul_f32 v[26:27], v[26:27], v[90:91] op_sel_hi:[1,0]
	v_pk_mul_f32 v[24:25], v[24:25], v[90:91] op_sel_hi:[1,0]
	v_pk_mul_f32 v[22:23], v[22:23], v[90:91] op_sel_hi:[1,0]
	v_pk_mul_f32 v[20:21], v[20:21], v[90:91] op_sel_hi:[1,0]
	v_pk_mul_f32 v[18:19], v[18:19], v[90:91] op_sel_hi:[1,0]
; DI float xor32_sum(float x) { const auto r_ = __builtin_amdgcn_permlane32_swap(__float_as_uint(x), __float_as_uint(x), false, false); return __uint_as_float(r_[0]) + __uint_as_float(r_[1]); }
; #define MFMA32(a, b, c) __builtin_amdgcn_mfma_f32_32x32x16_bf16((a), (b), (c), 0, 0, 0)
; DI bf16x8 packp(const f32x16& x, int s) { u32x4 p; p.x = pk2(x[8 * s], x[8 * s + 1]); p.y = pk2(x[8 * s + 2], x[8 * s + 3]); p.z = pk2(x[8 * s + 4], x[8 * s + 5]); p.w = pk2(x[8 * s + 6], x[8 * s + 7]); return __builtin_bit_cast(bf16x8, p); }
; DI bf16x8 lds2x4(const unsigned char* p) { const s16x4 a = *(const s16x4*)p, b = *(const s16x4*)(p + 16); return __builtin_shufflevector(a, b, 0, 1, 2, 3, 4, 5, 6, 7); }
; template <int MODE>
; DI void attn_tile64_far(const unsigned char* bp  , int r, int hh, bool bit, const bf16x8 (&qf)[8], const float* lutH, f32x16 (&o)[4], float& m, float& l) {
;     ...
;     float psum = 0.f;
; #pragma unroll
;     for (int i = 0; i < 16; ++i) { const float p0 = __builtin_amdgcn_exp2f(s0[i] - msub), p1 = __builtin_amdgcn_exp2f(s1[i] - msub); s0[i] = p0; s1[i] = p1; psum += p0 + p1; }
;     l += xor32_sum(psum);
;     const unsigned char* vp = bp + A_VOFF + r * 136 + 8 * hh;
; #pragma unroll
;     for (int s2 = 0; s2 < 2; ++s2) { const bf16x8 pb0 = packp(s0, s2), pb1 = packp(s1, s2);
; #pragma unroll
;         for (int dt = 0; dt < 4; ++dt) { const bf16x8 a0 = lds2x4(vp + dt * (32 * 136) + 32 * s2), a1 = lds2x4(vp + dt * (32 * 136) + 64 + 32 * s2);
;             o[dt] = MFMA32(a0, pb0, o[dt]); o[dt] = MFMA32(a1, pb1, o[dt]); } }
.LBB0_805:
	v_cndmask_b32_e64 v108, v199, v89, s[10:11]
	v_sub_f32_e32 v89, v219, v108
	v_exp_f32_e32 v109, v89
	v_sub_f32_e32 v89, v220, v108
	v_exp_f32_e32 v110, v89
	v_sub_f32_e32 v89, v218, v108
	v_sub_f32_e32 v2, v2, v108
	v_exp_f32_e32 v90, v89
	v_exp_f32_e32 v2, v2
	v_add_f32_e32 v91, v109, v110
	v_sub_f32_e32 v89, v217, v108
	v_sub_f32_e32 v88, v88, v108
	v_pk_add_f32 v[92:93], v[90:91], v[2:3]
	v_exp_f32_e32 v91, v89
	v_sub_f32_e32 v89, v216, v108
	v_exp_f32_e32 v111, v89
	v_sub_f32_e32 v89, v215, v108
	v_pk_add_f32 v[102:103], v[92:93], v[92:93] op_sel_hi:[0,1]
	v_exp_f32_e32 v92, v89
	v_sub_f32_e32 v89, v214, v108
	v_exp_f32_e32 v102, v89
	v_add_f32_e32 v93, v91, v111
	v_sub_f32_e32 v89, v213, v108
	v_sub_f32_e32 v87, v87, v108
	v_pk_add_f32 v[94:95], v[92:93], v[102:103]
	v_exp_f32_e32 v93, v89
	v_sub_f32_e32 v89, v101, v108
	v_exp_f32_e32 v103, v89
	v_sub_f32_e32 v89, v100, v108
	v_pk_add_f32 v[104:105], v[94:95], v[94:95] op_sel_hi:[0,1]
	v_exp_f32_e32 v94, v89
	v_sub_f32_e32 v89, v99, v108
	v_exp_f32_e32 v104, v89
	v_add_f32_e32 v95, v93, v103
	v_sub_f32_e32 v89, v98, v108
	v_sub_f32_e32 v86, v86, v108
	v_pk_add_f32 v[96:97], v[94:95], v[104:105]
	v_pk_add_f32 v[100:101], v[96:97], v[96:97] op_sel_hi:[0,1]
	v_exp_f32_e32 v95, v89
	v_exp_f32_e32 v105, v88
	v_exp_f32_e32 v96, v87
	v_exp_f32_e32 v100, v86
	v_add_f32_e32 v97, v95, v105
	v_cvt_pk_bf16_f32 v90, v109, v90
	v_cvt_pk_bf16_f32 v91, v91, v92
	v_cvt_pk_bf16_f32 v92, v93, v94
	v_cvt_pk_bf16_f32 v93, v95, v96
	v_pk_add_f32 v[98:99], v[96:97], v[100:101]
	s_waitcnt lgkmcnt(3)
	v_mfma_f32_32x32x16_bf16 v[66:81], v[224:227], v[90:93], v[66:81]
	ds_read2_b64 v[224:227], v242 offset0:192 offset1:194
	v_cvt_pk_bf16_f32 v86, v110, v2
	v_add_f32_e64 v106, v98, v98
	v_add_f32_e64 v107, v98, v99
	v_cvt_pk_bf16_f32 v89, v105, v100
	v_sub_f32_e32 v85, v85, v108
	v_sub_f32_e32 v83, v83, v108
	v_exp_f32_e32 v109, v85
	v_cvt_pk_bf16_f32 v88, v103, v104
	v_exp_f32_e32 v104, v83
	v_sub_f32_e32 v83, v84, v108
	v_sub_f32_e32 v82, v82, v108
	v_cvt_pk_bf16_f32 v87, v111, v102
	v_exp_f32_e32 v102, v83
	v_exp_f32_e32 v106, v82
	v_add_f32_e32 v103, v109, v104
	s_waitcnt lgkmcnt(3)
	v_mfma_f32_32x32x16_bf16 v[66:81], v[228:231], v[86:89], v[66:81]
	ds_read2_b64 v[228:231], v242 offset0:200 offset1:202
	v_add_f32_e64 v94, v102, v106
	v_add_f32_e64 v95, v103, v107
	v_sub_f32_e32 v15, v15, v108
	v_sub_f32_e32 v13, v13, v108
	v_exp_f32_e32 v103, v15
	v_exp_f32_e32 v107, v13
	s_waitcnt lgkmcnt(3)
	v_mfma_f32_32x32x16_bf16 v[50:65], v[232:235], v[90:93], v[50:65]
	ds_read2_b64 v[232:235], v243 offset0:224 offset1:226
	v_add_f32_e64 v98, v94, v94
	v_add_f32_e64 v99, v94, v95
	v_sub_f32_e32 v13, v14, v108
	v_sub_f32_e32 v12, v12, v108
	v_exp_f32_e32 v100, v13
	v_exp_f32_e32 v98, v12
	v_add_f32_e32 v101, v103, v107
	s_waitcnt lgkmcnt(3)
	v_mfma_f32_32x32x16_bf16 v[50:65], v[236:239], v[86:89], v[50:65]
	ds_read2_b64 v[236:239], v243 offset0:232 offset1:234
	v_add_f32_e64 v82, v100, v98
	v_add_f32_e64 v83, v101, v99
	v_sub_f32_e32 v11, v11, v108
	v_sub_f32_e32 v9, v9, v108
	v_exp_f32_e32 v99, v11
	v_exp_f32_e32 v110, v9
	s_waitcnt lgkmcnt(3)
	v_mfma_f32_32x32x16_bf16 v[34:49], v[224:227], v[90:93], v[34:49]
	ds_read2_b64 v[224:227], v240 offset0:132 offset1:134
	v_add_f32_e64 v94, v82, v82
	v_add_f32_e64 v95, v82, v83
	v_sub_f32_e32 v9, v10, v108
	v_sub_f32_e32 v8, v8, v108
	v_exp_f32_e32 v96, v9
	v_exp_f32_e32 v94, v8
	v_add_f32_e32 v97, v99, v110
	s_waitcnt lgkmcnt(3)
	v_mfma_f32_32x32x16_bf16 v[34:49], v[228:231], v[86:89], v[34:49]
	ds_read2_b64 v[228:231], v240 offset0:140 offset1:142
	v_add_f32_e64 v12, v96, v94
	v_add_f32_e64 v13, v97, v95
	v_sub_f32_e32 v7, v7, v108
	v_sub_f32_e32 v5, v5, v108
	v_sub_f32_e32 v4, v4, v108
	s_waitcnt lgkmcnt(3)
	v_mfma_f32_32x32x16_bf16 v[18:33], v[232:235], v[90:93], v[18:33]
	ds_read2_b64 v[232:235], v241 offset0:164 offset1:166
	v_add_f32_e64 v90, v12, v12
	v_add_f32_e64 v91, v12, v13
	v_exp_f32_e32 v93, v7
	v_exp_f32_e32 v92, v5
	v_sub_f32_e32 v90, v6, v108
	v_cvt_pk_bf16_f32 v6, v109, v102
	v_cvt_pk_bf16_f32 v7, v103, v100
	s_waitcnt lgkmcnt(3)
	v_mfma_f32_32x32x16_bf16 v[18:33], v[236:239], v[86:89], v[18:33]
	ds_read2_b64 v[236:239], v241 offset0:172 offset1:174
	v_cvt_pk_bf16_f32 v8, v99, v96
	v_cvt_pk_bf16_f32 v9, v93, v92
	v_exp_f32_e32 v5, v90
	v_exp_f32_e32 v90, v4
	v_cvt_pk_bf16_f32 v10, v104, v106
	v_cvt_pk_bf16_f32 v11, v107, v98
	s_waitcnt lgkmcnt(3)
	v_mfma_f32_32x32x16_bf16 v[66:81], v[224:227], v[6:9], v[66:81]
	ds_read2_b64 v[224:227], v242 offset0:196 offset1:198
	v_cvt_pk_bf16_f32 v12, v110, v94
	v_cvt_pk_bf16_f32 v13, v5, v90
	v_add_f32_e32 v93, v93, v5
	v_add_f32_e64 v4, v92, v90
	v_add_f32_e64 v5, v93, v91
	v_pk_add_f32 v[4:5], v[4:5], v[4:5] op_sel:[0,1] op_sel_hi:[1,0]
	s_waitcnt lgkmcnt(3)
	v_mfma_f32_32x32x16_bf16 v[66:81], v[228:231], v[10:13], v[66:81]
	ds_read2_b64 v[228:231], v242 offset0:204 offset1:206
	s_waitcnt lgkmcnt(3)
	v_mfma_f32_32x32x16_bf16 v[50:65], v[232:235], v[6:9], v[50:65]
	ds_read2_b64 v[232:235], v243 offset0:228 offset1:230
	v_mov_b32_e32 v2, v4
	s_nop 1
	v_permlane32_swap_b32_e32 v4, v2
	v_add_f32_e32 v2, v4, v2
	v_add_f32_e32 v181, v181, v2
	s_waitcnt lgkmcnt(3)
	v_mfma_f32_32x32x16_bf16 v[50:65], v[236:239], v[10:13], v[50:65]
	ds_read2_b64 v[236:239], v243 offset0:236 offset1:238
	s_waitcnt lgkmcnt(3)
	v_mfma_f32_32x32x16_bf16 v[34:49], v[224:227], v[6:9], v[34:49]
	s_waitcnt lgkmcnt(2)
	v_mfma_f32_32x32x16_bf16 v[34:49], v[228:231], v[10:13], v[34:49]
	s_waitcnt lgkmcnt(1)
	v_mfma_f32_32x32x16_bf16 v[18:33], v[232:235], v[6:9], v[18:33]
	s_waitcnt lgkmcnt(0)
	v_mfma_f32_32x32x16_bf16 v[18:33], v[236:239], v[10:13], v[18:33]

; DI float xor32_max(float x) { const auto r_ = __builtin_amdgcn_permlane32_swap(__float_as_uint(x), __float_as_uint(x), false, false); return fmaxf(__uint_as_float(r_[0]), __uint_as_float(r_[1])); }
; #define MFMA32(a, b, c) __builtin_amdgcn_mfma_f32_32x32x16_bf16((a), (b), (c), 0, 0, 0)
; template <int MODE>
; DI void attn_tile64_far(const unsigned char* bp  , int r, int hh, bool bit, const bf16x8 (&qf)[8], const float* lutH, f32x16 (&o)[4], float& m, float& l) {
;     f32x16 s0, s1;
; #pragma unroll
;     for (int i = 0; i < 16; ++i) { s0[i] = 0.f; s1[i] = 0.f; }
;     const unsigned char* kp = bp + r * 272 + 16 * hh;
; #pragma unroll
;     for (int kk = 0; kk < 8; ++kk) { const bf16x8 a0 = *(const bf16x8*)(kp + 32 * kk), a1 = *(const bf16x8*)(kp + 32 * 272 + 32 * kk); s0 = MFMA32(a0, qf[kk], s0); s1 = MFMA32(a1, qf[kk], s1); }
;     const float b31 = lutH[255];
;     float tmax = NEGF;
; #pragma unroll
;     for (int i = 0; i < 16; ++i) { s0[i] = s0[i] * QK_C1 + b31; s1[i] = s1[i] * QK_C1 + b31; tmax = fmaxf(tmax, fmaxf(s0[i], s1[i])); }
;     if (MODE == 0 && !bit) tmax = NEGF;
;     tmax = xor32_max(tmax);
;     const float mnew = fmaxf(m, tmax);
;     const float msub = (MODE == 0 && !bit) ? 3.0e38f : mnew;
;     if (__ballot(mnew != m) != 0ull) {
;         const float alpha = __builtin_amdgcn_exp2f(m - mnew);
;         l *= alpha; m = mnew;
; #pragma unroll
;         for (int dt = 0; dt < 4; ++dt)
; #pragma unroll
;             for (int i = 0; i < 16; ++i) o[dt][i] *= alpha;
;     }
.LBB0_827:
.LBB0_828:
	s_andn2_saveexec_b64 s[0:1], s[14:15]
	s_cbranch_execz .LBB0_832
	s_waitcnt lgkmcnt(0)
	ds_read_b32 v4, v202 offset:1020
	ds_read_b128 v[6:9], v2
	ds_read_b128 v[10:13], v2 offset:8704
	ds_read_b128 v[208:211], v2 offset:32
	ds_read_b128 v[212:215], v2 offset:8736
	ds_read_b128 v[216:219], v2 offset:64
	ds_read_b128 v[220:223], v2 offset:8768
	ds_read_b128 v[224:227], v2 offset:96
	ds_read_b128 v[228:231], v2 offset:8800
	ds_read_b128 v[232:235], v2 offset:128
	ds_read_b128 v[236:239], v2 offset:8832
	s_waitcnt lgkmcnt(9)
	v_mfma_f32_32x32x16_bf16 v[82:97], v[6:9], v[114:117], 0
	ds_read_b128 v[240:243], v2 offset:160
	s_waitcnt lgkmcnt(9)
	v_mfma_f32_32x32x16_bf16 v[98:113], v[10:13], v[114:117], 0
	ds_read_b128 v[6:9], v2 offset:8864
	s_waitcnt lgkmcnt(9)
	v_mfma_f32_32x32x16_bf16 v[82:97], v[208:211], v[118:121], v[82:97]
	ds_read_b128 v[10:13], v2 offset:192
	s_waitcnt lgkmcnt(9)
	v_mfma_f32_32x32x16_bf16 v[98:113], v[212:215], v[118:121], v[98:113]
	ds_read_b128 v[208:211], v2 offset:8896
	s_waitcnt lgkmcnt(9)
	v_mfma_f32_32x32x16_bf16 v[82:97], v[216:219], v[122:125], v[82:97]
	ds_read_b128 v[212:215], v2 offset:224
	s_waitcnt lgkmcnt(9)
	v_mfma_f32_32x32x16_bf16 v[98:113], v[220:223], v[122:125], v[98:113]
	ds_read_b128 v[216:219], v2 offset:8928
	s_waitcnt lgkmcnt(9)
	v_mfma_f32_32x32x16_bf16 v[82:97], v[224:227], v[126:129], v[82:97]
	s_waitcnt lgkmcnt(8)
	v_mfma_f32_32x32x16_bf16 v[98:113], v[228:231], v[126:129], v[98:113]
	s_waitcnt lgkmcnt(7)
	v_mfma_f32_32x32x16_bf16 v[82:97], v[232:235], v[130:133], v[82:97]
	s_waitcnt lgkmcnt(6)
	v_mfma_f32_32x32x16_bf16 v[98:113], v[236:239], v[130:133], v[98:113]
	s_waitcnt lgkmcnt(5)
	v_mfma_f32_32x32x16_bf16 v[82:97], v[240:243], v[134:137], v[82:97]
	s_waitcnt lgkmcnt(4)
	v_mfma_f32_32x32x16_bf16 v[98:113], v[6:9], v[134:137], v[98:113]
	s_waitcnt lgkmcnt(3)
	v_mfma_f32_32x32x16_bf16 v[82:97], v[10:13], v[138:141], v[82:97]
	s_waitcnt lgkmcnt(2)
	v_mfma_f32_32x32x16_bf16 v[98:113], v[208:211], v[138:141], v[98:113]
	s_waitcnt lgkmcnt(1)
	v_mfma_f32_32x32x16_bf16 v[82:97], v[212:215], v[142:145], v[82:97]
	s_waitcnt lgkmcnt(0)
	v_mfma_f32_32x32x16_bf16 v[98:113], v[216:219], v[142:145], v[98:113]
	s_nop 9
	v_add_u32_e32 v240, 0x4000, v181
	v_add_u32_e32 v241, 0x5000, v181
	v_add_u32_e32 v242, 0x6000, v181
	v_add_u32_e32 v243, 0x7000, v181
	ds_read2_b64 v[216:219], v240 offset0:128 offset1:130
	ds_read2_b64 v[220:223], v240 offset0:136 offset1:138
	ds_read2_b64 v[224:227], v241 offset0:160 offset1:162
	ds_read2_b64 v[228:231], v241 offset0:168 offset1:170
	ds_read2_b64 v[232:235], v242 offset0:192 offset1:194
	ds_read2_b64 v[236:239], v242 offset0:200 offset1:202
	v_fmamk_f32 v212, v82, 0x3e0293ee, v4
	v_fmamk_f32 v211, v83, 0x3e0293ee, v4
	v_fmamk_f32 v210, v84, 0x3e0293ee, v4
	v_fmamk_f32 v208, v85, 0x3e0293ee, v4
	v_fmamk_f32 v193, v86, 0x3e0293ee, v4
	v_fmamk_f32 v86, v90, 0x3e0293ee, v4
	v_fmamk_f32 v85, v91, 0x3e0293ee, v4
	v_fmamk_f32 v213, v98, 0x3e0293ee, v4
	v_fmamk_f32 v2, v99, 0x3e0293ee, v4
	v_max_f32_e32 v5, v212, v213
	v_max_f32_e32 v6, v211, v2
	v_fmamk_f32 v209, v100, 0x3e0293ee, v4
	v_fmamk_f32 v204, v101, 0x3e0293ee, v4
	v_max3_f32 v5, v5, s49, v6
	v_max_f32_e32 v6, v210, v209
	v_max_f32_e32 v7, v208, v204
	v_fmamk_f32 v102, v102, 0x3e0293ee, v4
	v_fmamk_f32 v101, v87, 0x3e0293ee, v4
	v_fmamk_f32 v100, v103, 0x3e0293ee, v4
	v_max3_f32 v5, v5, v6, v7
	v_max_f32_e32 v6, v193, v102
	v_max_f32_e32 v7, v101, v100
	v_fmamk_f32 v99, v88, 0x3e0293ee, v4
	v_fmamk_f32 v98, v104, 0x3e0293ee, v4
	v_fmamk_f32 v88, v89, 0x3e0293ee, v4
	v_fmamk_f32 v87, v105, 0x3e0293ee, v4
	v_max3_f32 v5, v5, v6, v7
	v_max_f32_e32 v6, v99, v98
	v_max_f32_e32 v7, v88, v87
	v_fmamk_f32 v84, v106, 0x3e0293ee, v4
	v_fmamk_f32 v83, v107, 0x3e0293ee, v4
	v_max3_f32 v5, v5, v6, v7
	v_max_f32_e32 v6, v86, v84
	v_max_f32_e32 v7, v85, v83
	v_fmamk_f32 v82, v92, 0x3e0293ee, v4
	v_fmamk_f32 v14, v108, 0x3e0293ee, v4
	v_fmamk_f32 v15, v93, 0x3e0293ee, v4
	v_fmamk_f32 v13, v109, 0x3e0293ee, v4
	v_max3_f32 v5, v5, v6, v7
	v_max_f32_e32 v6, v82, v14
	v_max_f32_e32 v7, v15, v13
	v_fmamk_f32 v12, v94, 0x3e0293ee, v4
	v_fmamk_f32 v10, v110, 0x3e0293ee, v4
	v_fmamk_f32 v11, v95, 0x3e0293ee, v4
	v_fmamk_f32 v9, v111, 0x3e0293ee, v4
	v_max3_f32 v5, v5, v6, v7
	v_max_f32_e32 v6, v12, v10
	v_max_f32_e32 v7, v11, v9
	v_max3_f32 v5, v5, v6, v7
	v_fmamk_f32 v8, v96, 0x3e0293ee, v4
	v_fmamk_f32 v7, v112, 0x3e0293ee, v4
	v_fmamk_f32 v6, v97, 0x3e0293ee, v4
	v_fmac_f32_e32 v4, 0x3e0293ee, v113
	v_max_f32_e32 v89, v8, v7
	v_max_f32_e32 v90, v6, v4
	v_max3_f32 v5, v5, v89, v90
	v_mov_b32_e32 v89, v5
	s_nop 1
	v_permlane32_swap_b32_e32 v5, v89
	v_max3_f32 v5, v192, v5, v89
	v_cmp_neq_f32_e32 vcc, v5, v192
	s_cbranch_vccz .LBB0_831
	v_sub_f32_e32 v89, v192, v5
	v_exp_f32_e32 v90, v89
	v_mov_b32_e32 v192, v5
	v_mul_f32_e32 v189, v189, v90
	v_pk_mul_f32 v[80:81], v[80:81], v[90:91] op_sel_hi:[1,0]
	v_pk_mul_f32 v[78:79], v[78:79], v[90:91] op_sel_hi:[1,0]
	v_pk_mul_f32 v[76:77], v[76:77], v[90:91] op_sel_hi:[1,0]
	v_pk_mul_f32 v[74:75], v[74:75], v[90:91] op_sel_hi:[1,0]
	v_pk_mul_f32 v[72:73], v[72:73], v[90:91] op_sel_hi:[1,0]
	v_pk_mul_f32 v[70:71], v[70:71], v[90:91] op_sel_hi:[1,0]
	v_pk_mul_f32 v[68:69], v[68:69], v[90:91] op_sel_hi:[1,0]
	v_pk_mul_f32 v[66:67], v[66:67], v[90:91] op_sel_hi:[1,0]
	v_pk_mul_f32 v[64:65], v[64:65], v[90:91] op_sel_hi:[1,0]
	v_pk_mul_f32 v[62:63], v[62:63], v[90:91] op_sel_hi:[1,0]
	v_pk_mul_f32 v[60:61], v[60:61], v[90:91] op_sel_hi:[1,0]
	v_pk_mul_f32 v[58:59], v[58:59], v[90:91] op_sel_hi:[1,0]
	v_pk_mul_f32 v[56:57], v[56:57], v[90:91] op_sel_hi:[1,0]
	v_pk_mul_f32 v[54:55], v[54:55], v[90:91] op_sel_hi:[1,0]
	v_pk_mul_f32 v[52:53], v[52:53], v[90:91] op_sel_hi:[1,0]
	v_pk_mul_f32 v[50:51], v[50:51], v[90:91] op_sel_hi:[1,0]
	v_pk_mul_f32 v[48:49], v[48:49], v[90:91] op_sel_hi:[1,0]
	v_pk_mul_f32 v[46:47], v[46:47], v[90:91] op_sel_hi:[1,0]
	v_pk_mul_f32 v[44:45], v[44:45], v[90:91] op_sel_hi:[1,0]
	v_pk_mul_f32 v[42:43], v[42:43], v[90:91] op_sel_hi:[1,0]
	v_pk_mul_f32 v[40:41], v[40:41], v[90:91] op_sel_hi:[1,0]
	v_pk_mul_f32 v[38:39], v[38:39], v[90:91] op_sel_hi:[1,0]
	v_pk_mul_f32 v[36:37], v[36:37], v[90:91] op_sel_hi:[1,0]
	v_pk_mul_f32 v[34:35], v[34:35], v[90:91] op_sel_hi:[1,0]
	v_pk_mul_f32 v[32:33], v[32:33], v[90:91] op_sel_hi:[1,0]
	v_pk_mul_f32 v[30:31], v[30:31], v[90:91] op_sel_hi:[1,0]
	v_pk_mul_f32 v[28:29], v[28:29], v[90:91] op_sel_hi:[1,0]
	v_pk_mul_f32 v[26:27], v[26:27], v[90:91] op_sel_hi:[1,0]
	v_pk_mul_f32 v[24:25], v[24:25], v[90:91] op_sel_hi:[1,0]
	v_pk_mul_f32 v[22:23], v[22:23], v[90:91] op_sel_hi:[1,0]
	v_pk_mul_f32 v[20:21], v[20:21], v[90:91] op_sel_hi:[1,0]
	v_pk_mul_f32 v[18:19], v[18:19], v[90:91] op_sel_hi:[1,0]
; DI float xor32_sum(float x) { const auto r_ = __builtin_amdgcn_permlane32_swap(__float_as_uint(x), __float_as_uint(x), false, false); return __uint_as_float(r_[0]) + __uint_as_float(r_[1]); }
; #define MFMA32(a, b, c) __builtin_amdgcn_mfma_f32_32x32x16_bf16((a), (b), (c), 0, 0, 0)
; DI bf16x8 packp(const f32x16& x, int s) { u32x4 p; p.x = pk2(x[8 * s], x[8 * s + 1]); p.y = pk2(x[8 * s + 2], x[8 * s + 3]); p.z = pk2(x[8 * s + 4], x[8 * s + 5]); p.w = pk2(x[8 * s + 6], x[8 * s + 7]); return __builtin_bit_cast(bf16x8, p); }
; DI bf16x8 lds2x4(const unsigned char* p) { const s16x4 a = *(const s16x4*)p, b = *(const s16x4*)(p + 16); return __builtin_shufflevector(a, b, 0, 1, 2, 3, 4, 5, 6, 7); }
; template <int MODE>
; DI void attn_tile64_far(const unsigned char* bp  , int r, int hh, bool bit, const bf16x8 (&qf)[8], const float* lutH, f32x16 (&o)[4], float& m, float& l) {
;     ...
;     float psum = 0.f;
; #pragma unroll
;     for (int i = 0; i < 16; ++i) { const float p0 = __builtin_amdgcn_exp2f(s0[i] - msub), p1 = __builtin_amdgcn_exp2f(s1[i] - msub); s0[i] = p0; s1[i] = p1; psum += p0 + p1; }
;     l += xor32_sum(psum);
;     const unsigned char* vp = bp + A_VOFF + r * 136 + 8 * hh;
; #pragma unroll
;     for (int s2 = 0; s2 < 2; ++s2) { const bf16x8 pb0 = packp(s0, s2), pb1 = packp(s1, s2);
; #pragma unroll
;         for (int dt = 0; dt < 4; ++dt) { const bf16x8 a0 = lds2x4(vp + dt * (32 * 136) + 32 * s2), a1 = lds2x4(vp + dt * (32 * 136) + 64 + 32 * s2);
;             o[dt] = MFMA32(a0, pb0, o[dt]); o[dt] = MFMA32(a1, pb1, o[dt]); } }
.LBB0_831:
	v_sub_f32_e32 v89, v212, v5
	v_exp_f32_e32 v110, v89
	v_sub_f32_e32 v89, v213, v5
	v_exp_f32_e32 v111, v89
	v_sub_f32_e32 v89, v211, v5
	v_sub_f32_e32 v2, v2, v5
	v_exp_f32_e32 v92, v89
	v_exp_f32_e32 v2, v2
	v_add_f32_e32 v93, v110, v111
	v_sub_f32_e32 v89, v210, v5
	v_sub_f32_e32 v88, v88, v5
	v_pk_add_f32 v[90:91], v[92:93], v[2:3]
	v_exp_f32_e32 v93, v89
	v_sub_f32_e32 v89, v209, v5
	v_exp_f32_e32 v112, v89
	v_sub_f32_e32 v89, v208, v5
	v_pk_add_f32 v[104:105], v[90:91], v[90:91] op_sel_hi:[0,1]
	v_exp_f32_e32 v94, v89
	v_sub_f32_e32 v89, v204, v5
	v_exp_f32_e32 v104, v89
	v_add_f32_e32 v95, v93, v112
	v_sub_f32_e32 v89, v193, v5
	v_pk_add_f32 v[90:91], v[94:95], v[104:105]
	v_exp_f32_e32 v95, v89
	v_sub_f32_e32 v89, v102, v5
	v_exp_f32_e32 v105, v89
	v_sub_f32_e32 v89, v101, v5
	v_pk_add_f32 v[106:107], v[90:91], v[90:91] op_sel_hi:[0,1]
	v_exp_f32_e32 v96, v89
	v_sub_f32_e32 v89, v100, v5
	v_exp_f32_e32 v106, v89
	v_add_f32_e32 v97, v95, v105
	v_sub_f32_e32 v89, v99, v5
	v_sub_f32_e32 v87, v87, v5
	v_pk_add_f32 v[90:91], v[96:97], v[106:107]
	v_exp_f32_e32 v97, v89
	v_sub_f32_e32 v89, v98, v5
	v_pk_add_f32 v[100:101], v[90:91], v[90:91] op_sel_hi:[0,1]
	v_exp_f32_e32 v107, v89
	v_exp_f32_e32 v98, v88
	v_exp_f32_e32 v100, v87
	v_add_f32_e32 v99, v97, v107
	v_sub_f32_e32 v86, v86, v5
	v_cvt_pk_bf16_f32 v92, v110, v92
	v_pk_add_f32 v[102:103], v[98:99], v[100:101]
	v_cvt_pk_bf16_f32 v93, v93, v94
	v_cvt_pk_bf16_f32 v94, v95, v96
	v_cvt_pk_bf16_f32 v95, v97, v98
	v_exp_f32_e32 v110, v86
	v_cvt_pk_bf16_f32 v86, v111, v2
	v_pk_add_f32 v[108:109], v[102:103], v[102:103] op_sel_hi:[0,1]
	s_waitcnt lgkmcnt(5)
	v_mfma_f32_32x32x16_bf16 v[66:81], v[216:219], v[92:95], v[66:81]
	ds_read2_b64 v[216:219], v243 offset0:224 offset1:226
	v_cvt_pk_bf16_f32 v89, v107, v100
	v_sub_f32_e32 v84, v84, v5
	v_cvt_pk_bf16_f32 v88, v105, v106
	v_exp_f32_e32 v106, v84
	v_sub_f32_e32 v84, v85, v5
	v_sub_f32_e32 v83, v83, v5
	v_exp_f32_e32 v90, v84
	v_exp_f32_e32 v108, v83
	v_cvt_pk_bf16_f32 v87, v112, v104
	v_add_f32_e32 v91, v110, v106
	v_sub_f32_e32 v82, v82, v5
	s_waitcnt lgkmcnt(5)
	v_mfma_f32_32x32x16_bf16 v[66:81], v[220:223], v[86:89], v[66:81]
	ds_read2_b64 v[220:223], v243 offset0:232 offset1:234
	v_add_f32_e64 v84, v90, v108
	v_add_f32_e64 v85, v91, v109
	v_exp_f32_e32 v91, v82
	v_sub_f32_e32 v14, v14, v5
	v_exp_f32_e32 v109, v14
	v_sub_f32_e32 v14, v15, v5
	s_waitcnt lgkmcnt(5)
	v_mfma_f32_32x32x16_bf16 v[50:65], v[224:227], v[92:95], v[50:65]
	ds_read2_b64 v[224:227], v240 offset0:132 offset1:134
	v_add_f32_e64 v100, v84, v84
	v_add_f32_e64 v101, v84, v85
	v_sub_f32_e32 v13, v13, v5
	v_exp_f32_e32 v102, v14
	v_exp_f32_e32 v100, v13
	v_add_f32_e32 v103, v91, v109
	v_sub_f32_e32 v12, v12, v5
	s_waitcnt lgkmcnt(5)
	v_mfma_f32_32x32x16_bf16 v[50:65], v[228:231], v[86:89], v[50:65]
	ds_read2_b64 v[228:231], v241 offset0:164 offset1:166
	v_add_f32_e64 v14, v102, v100
	v_add_f32_e64 v15, v103, v101
	v_add_f32_e64 v104, v14, v14
	v_add_f32_e64 v105, v14, v15
	v_exp_f32_e32 v101, v12
	v_sub_f32_e32 v10, v10, v5
	s_waitcnt lgkmcnt(5)
	v_mfma_f32_32x32x16_bf16 v[34:49], v[232:235], v[92:95], v[34:49]
	ds_read2_b64 v[232:235], v241 offset0:172 offset1:174
	v_sub_f32_e32 v9, v9, v5
	v_exp_f32_e32 v104, v9
	v_sub_f32_e32 v8, v8, v5
	v_sub_f32_e32 v6, v6, v5
	v_sub_f32_e32 v7, v7, v5
	v_sub_f32_e32 v4, v4, v5
	s_waitcnt lgkmcnt(5)
	v_mfma_f32_32x32x16_bf16 v[34:49], v[236:239], v[86:89], v[34:49]
	ds_read2_b64 v[236:239], v242 offset0:196 offset1:198
	v_exp_f32_e32 v98, v10
	v_sub_f32_e32 v10, v11, v5
	v_exp_f32_e32 v96, v10
	v_cvt_pk_bf16_f32 v5, v109, v100
	v_add_f32_e32 v97, v101, v98
	v_pk_add_f32 v[10:11], v[96:97], v[104:105]
	s_waitcnt lgkmcnt(5)
	v_mfma_f32_32x32x16_bf16 v[18:33], v[216:219], v[92:95], v[18:33]
	ds_read2_b64 v[216:219], v242 offset0:204 offset1:206
	v_add_f32_e64 v92, v10, v10
	v_add_f32_e64 v93, v10, v11
	v_exp_f32_e32 v94, v8
	v_cvt_pk_bf16_f32 v12, v110, v90
	v_cvt_pk_bf16_f32 v13, v91, v102
	v_cvt_pk_bf16_f32 v14, v101, v96
	v_exp_f32_e32 v92, v4
	s_waitcnt lgkmcnt(5)
	v_mfma_f32_32x32x16_bf16 v[18:33], v[220:223], v[86:89], v[18:33]
	ds_read2_b64 v[220:223], v240 offset0:140 offset1:142
	v_exp_f32_e32 v86, v6
	v_exp_f32_e32 v87, v7
	v_cvt_pk_bf16_f32 v4, v106, v108
	v_cvt_pk_bf16_f32 v6, v98, v104
	v_cvt_pk_bf16_f32 v15, v94, v86
	v_cvt_pk_bf16_f32 v7, v87, v92
	s_waitcnt lgkmcnt(5)
	v_mfma_f32_32x32x16_bf16 v[66:81], v[224:227], v[12:15], v[66:81]
	ds_read2_b64 v[224:227], v243 offset0:228 offset1:230
	v_add_f32_e32 v87, v94, v87
	s_waitcnt lgkmcnt(5)
	v_mfma_f32_32x32x16_bf16 v[50:65], v[228:231], v[12:15], v[50:65]
	ds_read2_b64 v[228:231], v243 offset0:236 offset1:238
	s_waitcnt lgkmcnt(5)
	v_mfma_f32_32x32x16_bf16 v[50:65], v[232:235], v[4:7], v[50:65]
	s_waitcnt lgkmcnt(4)
	v_mfma_f32_32x32x16_bf16 v[34:49], v[236:239], v[12:15], v[34:49]
	s_waitcnt lgkmcnt(3)
	v_mfma_f32_32x32x16_bf16 v[34:49], v[216:219], v[4:7], v[34:49]
	s_waitcnt lgkmcnt(2)
	v_mfma_f32_32x32x16_bf16 v[66:81], v[220:223], v[4:7], v[66:81]
	s_waitcnt lgkmcnt(1)
	v_mfma_f32_32x32x16_bf16 v[18:33], v[224:227], v[12:15], v[18:33]
	v_add_f32_e64 v8, v86, v92
	v_add_f32_e64 v9, v87, v93
	v_pk_add_f32 v[8:9], v[8:9], v[8:9] op_sel:[0,1] op_sel_hi:[1,0]
	s_nop 0
	v_mov_b32_e32 v2, v8
	s_nop 1
	v_permlane32_swap_b32_e32 v8, v2
	s_waitcnt lgkmcnt(0)
	v_mfma_f32_32x32x16_bf16 v[18:33], v[228:231], v[4:7], v[18:33]
	v_add_f32_e32 v2, v8, v2
	v_add_f32_e32 v189, v189, v2
